# v22 plus thin-phase unit tops without vmcnt(0) before the workgroup barrier
# speedup vs baseline: 1.0025x; 1.0025x over previous
.LBB0_454:
	s_lshl_b32 s10, s12, 4
	s_lshl_b32 s13, s12, 6
	s_and_b32 s10, s10, 0xfffff000
	s_and_b32 s13, s13, 0xfc0
	s_or_b32 s13, s10, s13
	s_nop 0
	s_barrier
	s_and_saveexec_b64 s[14:15], s[0:1]
	s_cbranch_execz .LBB0_456
	v_or_b32_e32 v4, s13, v48
	v_mov_b64_e32 v[2:3], s[8:9]
	v_mad_i64_i32 v[2:3], s[16:17], v4, s22, v[2:3]
	v_mov_b32_e32 v23, v11
	v_lshl_add_u64 v[2:3], v[2:3], 0, v[22:23]
	v_add_co_u32_e32 v2, vcc, 0xc000, v2
	s_nop 1
	v_addc_co_u32_e32 v3, vcc, 0, v3, vcc
	global_load_dwordx4 v[124:127], v[2:3], off offset:2560

.LBB0_1237:
	s_lshl_b32 s10, s12, 4
	s_lshl_b32 s13, s12, 6
	s_and_b32 s10, s10, 0xfffff000
	s_and_b32 s13, s13, 0xfc0
	s_or_b32 s13, s10, s13
	s_nop 0
	s_barrier
	s_and_saveexec_b64 s[14:15], s[4:5]
	s_cbranch_execz .LBB0_1239
	v_or_b32_e32 v4, s13, v47
	v_mov_b64_e32 v[2:3], s[2:3]
	v_mad_i64_i32 v[2:3], s[16:17], v4, s23, v[2:3]
	v_mov_b32_e32 v23, v11
	v_lshl_add_u64 v[2:3], v[2:3], 0, v[22:23]
	v_add_co_u32_e32 v2, vcc, 0xc000, v2
	s_nop 1
	v_addc_co_u32_e32 v3, vcc, 0, v3, vcc
	global_load_dwordx4 v[124:127], v[2:3], off offset:2560
